# LN residual loads batched + barrier census loads batched (no x-loop change)
# baseline (speedup 1.0000x reference)
; DI unsigned xb_ld(unsigned* p)              { return __hip_atomic_load(p, __ATOMIC_RELAXED, __HIP_MEMORY_SCOPE_AGENT); }
; DI void xcd_barrier_complete(unsigned* bar, unsigned x, unsigned& nloc, unsigned& nx) {
;     ...
;     unsigned sum, cnt, mine, sp = 0u;
;     for (;;) {
;         sum = 0u; cnt = 0u; mine = 0u;
; #pragma unroll
;         for (unsigned j = 0; j < 16; ++j) { const unsigned c = xb_ld(&bar[XB_XCNT(j)]); sum += c; cnt += (c > 0u) ? 1u : 0u; mine = (j == x) ? c : mine; }
;         if (sum == G) break;
;         __builtin_amdgcn_s_sleep(1);
;         if ((++sp & 255u) == 0u) { if (xb_ld(&bar[XB_TMO])) break; if (sp > XB_SPIN_CAP) { atomicAdd(&bar[XB_TMO], 1u); break; } }
;     }
.LBB0_568:
	s_mov_b64 s[16:17], -1
	s_mov_b64 s[18:19], -1
	v_readlane_b32 s6, v253, 40
	v_readlane_b32 s7, v253, 41
	s_nop 4
	global_load_dword v0, v97, s[6:7] sc1
	v_readlane_b32 s6, v253, 42
	v_readlane_b32 s7, v253, 43
	s_nop 4
	global_load_dword v1, v97, s[6:7] sc1
	v_readlane_b32 s6, v253, 44
	v_readlane_b32 s7, v253, 45
	s_nop 4
	global_load_dword v2, v97, s[6:7] sc1
	v_readlane_b32 s6, v253, 46
	v_readlane_b32 s7, v253, 47
	s_nop 4
	global_load_dword v3, v97, s[6:7] sc1
	v_readlane_b32 s6, v253, 48
	v_readlane_b32 s7, v253, 49
	s_nop 4
	global_load_dword v4, v97, s[6:7] sc1
	v_readlane_b32 s6, v253, 50
	v_readlane_b32 s7, v253, 51
	s_nop 4
	global_load_dword v5, v97, s[6:7] sc1
	v_readlane_b32 s6, v253, 52
	v_readlane_b32 s7, v253, 53
	s_nop 4
	global_load_dword v6, v97, s[6:7] sc1
	v_readlane_b32 s6, v253, 54
	v_readlane_b32 s7, v253, 55
	s_nop 4
	global_load_dword v7, v97, s[6:7] sc1
	v_readlane_b32 s6, v253, 56
	v_readlane_b32 s7, v253, 57
	s_nop 4
	global_load_dword v8, v97, s[6:7] sc1
	v_readlane_b32 s6, v253, 58
	v_readlane_b32 s7, v253, 59
	s_nop 4
	global_load_dword v9, v97, s[6:7] sc1
	v_readlane_b32 s6, v253, 60
	v_readlane_b32 s7, v253, 61
	s_nop 4
	global_load_dword v10, v97, s[6:7] sc1
	v_readlane_b32 s6, v253, 62
	v_readlane_b32 s7, v253, 63
	s_nop 4
	global_load_dword v11, v97, s[6:7] sc1
	v_readlane_b32 s6, v254, 0
	v_readlane_b32 s7, v254, 1
	s_nop 4
	global_load_dword v12, v97, s[6:7] sc1
	v_readlane_b32 s6, v254, 2
	v_readlane_b32 s7, v254, 3
	s_nop 4
	global_load_dword v13, v97, s[6:7] sc1
	v_readlane_b32 s6, v254, 4
	v_readlane_b32 s7, v254, 5
	s_nop 4
	global_load_dword v14, v97, s[6:7] sc1
	v_readlane_b32 s6, v254, 6
	v_readlane_b32 s7, v254, 7
	s_nop 4
	global_load_dword v15, v97, s[6:7] sc1
	s_waitcnt vmcnt(0)
	v_add_u32_e32 v16, v1, v0
	v_add_u32_e32 v16, v16, v2
	v_add_u32_e32 v16, v16, v3
	v_add_u32_e32 v16, v16, v4
	v_add_u32_e32 v16, v16, v5
	v_add_u32_e32 v16, v16, v6
	v_add_u32_e32 v16, v16, v7
	v_add_u32_e32 v16, v16, v8
	v_add_u32_e32 v16, v16, v9
	v_add_u32_e32 v16, v16, v10
	v_add_u32_e32 v16, v16, v11
	v_add_u32_e32 v16, v16, v12
	v_add_u32_e32 v16, v16, v13
	v_add_u32_e32 v16, v16, v14
	v_add_u32_e32 v16, v16, v15
	v_cmp_eq_u32_e32 vcc, s3, v16
	s_cbranch_vccnz .LBB0_567
	s_and_b32 s5, s4, 0xff
	s_cmp_eq_u32 s5, 0
	s_mov_b64 s[20:21], -1
	s_sleep 1
	s_cbranch_scc1 .LBB0_572
	s_and_b64 vcc, exec, s[20:21]
	s_cbranch_vccz .LBB0_567

; DI unsigned xb_ld(unsigned* p)              { return __hip_atomic_load(p, __ATOMIC_RELAXED, __HIP_MEMORY_SCOPE_AGENT); }
; __global__ void __launch_bounds__(NTHREADS, 2) mega_fwd(Args a) {
;     ...
;             if (ph == 0 && a.ph_hi - a.ph_lo > 1 && G == 256) {
;                 unsigned* bw = (unsigned*)(ws + WS_CTL); bool ok = true;
; #pragma unroll
;                 for (int j = 0; j < 16; ++j) { const unsigned cnt = xb_ld(&bw[XB_XCNT(j)]); ok = ok && (cnt == (j < 8 ? 32u : 0u)); }
;                 if (ok) { cv = (int)(misc[2] * 8u + xbar.x); grouped = true; }
;             }
.LBB0_641:
	s_cmp_eq_u32 s33, 0
	v_readlane_b32 s4, v254, 50
	s_cselect_b64 s[0:1], -1, 0
	v_readlane_b32 s5, v254, 51
	s_and_b64 s[0:1], s[0:1], s[4:5]
	s_andn2_b64 vcc, exec, s[0:1]
	s_waitcnt lgkmcnt(0)
	s_cbranch_vccnz .LBB0_10
	v_readlane_b32 s4, v253, 40
	v_readlane_b32 s5, v253, 41
	s_nop 4
	global_load_dword v0, v97, s[4:5] sc1
	v_readlane_b32 s4, v253, 42
	v_readlane_b32 s5, v253, 43
	s_nop 4
	global_load_dword v1, v97, s[4:5] sc1
	v_readlane_b32 s4, v253, 44
	v_readlane_b32 s5, v253, 45
	s_nop 4
	global_load_dword v2, v97, s[4:5] sc1
	v_readlane_b32 s4, v253, 46
	v_readlane_b32 s5, v253, 47
	s_nop 4
	global_load_dword v3, v97, s[4:5] sc1
	v_readlane_b32 s4, v253, 48
	v_readlane_b32 s5, v253, 49
	s_nop 4
	global_load_dword v4, v97, s[4:5] sc1
	v_readlane_b32 s4, v253, 50
	v_readlane_b32 s5, v253, 51
	s_nop 4
	global_load_dword v5, v97, s[4:5] sc1
	v_readlane_b32 s4, v253, 52
	v_readlane_b32 s5, v253, 53
	s_nop 4
	global_load_dword v6, v97, s[4:5] sc1
	v_readlane_b32 s4, v253, 54
	v_readlane_b32 s5, v253, 55
	s_nop 4
	global_load_dword v7, v97, s[4:5] sc1
	v_readlane_b32 s4, v253, 56
	v_readlane_b32 s5, v253, 57
	s_nop 4
	global_load_dword v8, v97, s[4:5] sc1
	v_readlane_b32 s4, v253, 58
	v_readlane_b32 s5, v253, 59
	s_nop 4
	global_load_dword v9, v97, s[4:5] sc1
	v_readlane_b32 s4, v253, 60
	v_readlane_b32 s5, v253, 61
	s_nop 4
	global_load_dword v10, v97, s[4:5] sc1
	v_readlane_b32 s4, v253, 62
	v_readlane_b32 s5, v253, 63
	s_nop 4
	global_load_dword v11, v97, s[4:5] sc1
	v_readlane_b32 s4, v254, 0
	v_readlane_b32 s5, v254, 1
	s_nop 4
	global_load_dword v12, v97, s[4:5] sc1
	v_readlane_b32 s4, v254, 2
	v_readlane_b32 s5, v254, 3
	s_nop 4
	global_load_dword v13, v97, s[4:5] sc1
	v_readlane_b32 s4, v254, 4
	v_readlane_b32 s5, v254, 5
	s_nop 4
	global_load_dword v14, v97, s[4:5] sc1
	v_readlane_b32 s4, v254, 6
	v_readlane_b32 s5, v254, 7
	s_nop 4
	global_load_dword v15, v97, s[4:5] sc1
	s_waitcnt vmcnt(0)
	v_xor_b32_e32 v0, 32, v0
	v_xor_b32_e32 v1, 32, v1
	v_xor_b32_e32 v2, 32, v2
	v_xor_b32_e32 v3, 32, v3
	v_xor_b32_e32 v4, 32, v4
	v_xor_b32_e32 v5, 32, v5
	v_xor_b32_e32 v6, 32, v6
	v_xor_b32_e32 v7, 32, v7
	v_or3_b32 v16, v0, v1, v2
	v_or3_b32 v16, v16, v3, v4
	v_or3_b32 v16, v16, v5, v6
	v_or3_b32 v16, v16, v7, v8
	v_or3_b32 v16, v16, v9, v10
	v_or3_b32 v16, v16, v11, v12
	v_or3_b32 v16, v16, v13, v14
	v_or_b32_e32 v16, v16, v15
	v_cmp_ne_u32_e32 vcc, 0, v16
	s_cbranch_vccnz .LBB0_10
	v_readlane_b32 s0, v254, 61
	v_readlane_b32 s1, v253, 10
	s_nop 0
	v_mov_b32_e32 v0, s0
	ds_read_b32 v0, v0
	s_waitcnt lgkmcnt(0)
	v_readfirstlane_b32 s0, v0
	s_lshl_b32 s0, s0, 3
	s_add_i32 s2, s0, s1
	s_mov_b64 s[0:1], -1
	v_writelane_b32 v255, s0, 4
	s_nop 1
	v_writelane_b32 v255, s1, 5
	s_branch .LBB0_10
